# attA unit prologue: all eight LDS-DMA loads of the first two K/V tiles issued before the wait for the Q fragments (counted wait instead of vmcnt(0))
# speedup vs baseline: 1.0046x; 1.0046x over previous
; __device__ __forceinline__ void unit(LAS unsigned char* lds, bf16_t* P1, const bf16_t* vaT, int b, int h, int qblk, float lam, const float* subln_w, const float* khalf) {
;     const int tid = threadIdx.x, lane = tid & 63, wid = __builtin_amdgcn_readfirstlane(tid >> 6), r32 = lane & 31, hi = lane >> 5;
;     const int mi = wid >> 2, qs = wid & 3;
;     const int qrow = qblk * 128 + qs * 32 + r32;
;     const size_t rowbase = (size_t)b * SEQ;
;     bf16x8 qf[4];
;     { const bf16_t* qp = P1 + (rowbase + qrow) * LDP + C_QA + (2 * h + mi) * 64 + hi * 8;
; #pragma unroll
;       for (int ks = 0; ks < 4; ++ks) qf[ks] = *(const bf16x8*)(qp + ks * 16); }
;     const float sl2 = ex2(-(float)(h + 1)) * LOG2E;
;     const float sl2h = sl2 * (float)(4 * hi);
;     float qbound;
;     { float q2 = 0.f;
; #pragma unroll
;       for (int ks = 0; ks < 4; ++ks)
; #pragma unroll
;           for (int e = 0; e < 8; ++e) { const float v = __uint_as_float((unsigned)(unsigned short)qf[ks][e] << 16); q2 += v * v; }
;       q2 += __shfl_xor(q2, 32);
;       const float* kh = khalf + (b * 16 + 2 * h + mi) * 2;
;       qbound = sqrtf(q2 * (kh[0] + kh[1])) * 1.01f + 0.05f; }
;     volatile LAS int* dflag = (volatile LAS int*)(lds + 4 * STG);
;     f32x16 O[4];
; #pragma unroll
;     for (int d = 0; d < 4; ++d)
; #pragma unroll
;         for (int r = 0; r < 16; ++r) O[d][r] = 0.f;
;     float m = -INFINITY, l = 0.f;
;     const int NT = 2 * qblk + 2;
;     const char* kbase = (const char*)(P1 + rowbase * LDP + C_KA + h * 128);
;     const char* vbase = (const char*)(vaT + (size_t)(h * 128) * MTOK + rowbase);
;     unsigned kso0, kso1, vso0, vso1;
;     { const int rk0 = (2 * wid) * 4 + (lane >> 4), rk1 = rk0 + 4, sl = lane & 15;
;       kso0 = (unsigned)((rk0 * LDP + ((sl ^ (rk0 & 15)) * 8)) * 2); kso1 = (unsigned)((rk1 * LDP + ((sl ^ (rk1 & 15)) * 8)) * 2);
;       const int d0 = (2 * wid) * 8 + (lane >> 3), d1 = d0 + 8, sv = lane & 7;
;       vso0 = (unsigned)((d0 * MTOK + ((sv ^ ((d0 >> 1) & 7)) * 8)) * 2); vso1 = (unsigned)((d1 * MTOK + ((sv ^ ((d1 >> 1) & 7)) * 8)) * 2); }
;     ...
;     unsigned koff[4], voff[4];
; #pragma unroll
;     for (int ks = 0; ks < 4; ++ks) koff[ks] = (unsigned)(r32 * 256 + (((mi * 8 + 2 * ks + hi) ^ (r32 & 15)) * 16));
; #pragma unroll
;     for (int q = 0; q < 4; ++q) voff[q] = (unsigned)(VOFF + r32 * 128 + (((2 * q + hi) ^ ((r32 >> 1) & 7)) * 16));
.LBB0_395:
	v_readfirstlane_b32 s61, v176
	s_and_b32 s2, s5, 31
	s_lshr_b32 s10, s61, 1
	s_xor_b32 s3, s2, 31
	s_and_b32 s76, s10, 0x60
	s_lshl_b32 s59, s3, 7
	v_or_b32_e32 v123, s76, v114
	v_or_b32_e32 v125, s59, v123
	s_lshl_b32 s60, s72, 12
	v_or_b32_e32 v0, s60, v125
	s_lshr_b32 s70, s61, 8
	v_mul_u32_u24_e32 v0, 0x1a00, v0
	s_lshl_b32 s10, s4, 1
	v_lshlrev_b32_e32 v0, 1, v0
	s_add_i32 s42, s70, s10
	v_lshl_add_u64 v[2:3], s[78:79], 0, v[0:1]
	s_lshl_b32 s10, s42, 7
	v_lshl_add_u64 v[2:3], v[2:3], 0, s[10:11]
	v_lshlrev_b32_e32 v0, 1, v116
	v_lshl_add_u64 v[2:3], v[2:3], 0, v[0:1]
	global_load_dwordx4 v[98:101], v[2:3], off
	global_load_dwordx4 v[102:105], v[2:3], off offset:32
	global_load_dwordx4 v[106:109], v[2:3], off offset:64
	global_load_dwordx4 v[110:113], v[2:3], off offset:96
	s_lshl_b32 s10, s72, 4
	s_add_i32 s42, s42, s10
	s_lshl_b32 s10, s42, 1
	s_lshr_b32 s77, s61, 6
	s_lshl_b64 s[42:43], s[10:11], 2
	s_add_u32 s42, s68, s42
	s_addc_u32 s43, s69, s43
	s_lshl_b32 s71, s3, 1
	s_mul_i32 s80, s72, 0x3400000
	s_add_u32 s73, s78, s80
	s_addc_u32 s74, s79, 0
	s_lshl_b32 s10, s4, 7
	s_lshl_b64 s[44:45], s[10:11], 15
	global_load_dwordx2 v[2:3], v1, s[42:43] offset:2304
	s_add_u32 s75, s6, s44
	v_lshl_or_b32 v0, s77, 3, v147
	s_movk_i32 s42, 0x3400
	s_addc_u32 s82, s7, s45
	v_mul_lo_u32 v6, v0, s42
	s_lshl_b64 s[42:43], s[10:11], 1
	v_or_b32_e32 v4, 4, v0
	v_bitop3_b32 v5, v0, v148, 11 bitop3:0x6c
	v_bitop3_b32 v0, v0, v176, 4 bitop3:0x36
	s_add_u32 s73, s73, s42
	v_lshlrev_b32_e32 v0, 3, v0
	s_addc_u32 s74, s74, s43
	s_lshl_b32 s81, s72, 13
	v_and_b32_e32 v10, 0x78, v0
	v_lshl_or_b32 v0, s77, 4, v149
	s_add_u32 s75, s75, s81
	v_mul_lo_u32 v4, v4, s47
	v_or_b32_e32 v9, 8, v0
	s_addc_u32 s82, s82, 0
	s_lshl_b32 s10, s77, 11
	v_or_b32_e32 v7, v10, v4
	v_lshl_or_b32 v4, v0, 15, v150
	v_lshrrev_b32_e32 v0, 1, v9
	s_add_i32 s72, s10, 0
	s_or_b32 s10, s59, 64
	v_xor_b32_e32 v0, v0, v176
	s_mul_i32 s83, s10, 0x3400
	v_lshlrev_b32_e32 v0, 4, v0
	v_lshlrev_b32_e32 v11, 4, v5
	s_add_u32 s84, s73, s83
	v_and_b32_e32 v12, 0x70, v0
	v_or_b32_e32 v0, v11, v6
	s_addc_u32 s85, s74, 0
	v_lshl_add_u64 v[14:15], s[84:85], 0, v[0:1]
	v_lshlrev_b32_e32 v8, 1, v7
	v_lshl_or_b32 v6, v9, 15, v12
	s_lshl_b32 s10, s10, 1
	v_lshl_add_u64 v[14:15], v[14:15], 0, s[18:19]
	s_mov_b32 m0, s72
	v_mov_b32_e32 v9, v1
	s_add_u32 s86, s75, s10
	global_load_lds_dwordx4 v[14:15], off
	v_lshl_add_u64 v[14:15], s[84:85], 0, v[8:9]
	s_addc_u32 s87, s82, 0
	v_lshl_add_u64 v[14:15], v[14:15], 0, s[18:19]
	s_add_i32 m0, s72, 0x400
	s_mul_i32 s10, s3, 0x1a0000
	global_load_lds_dwordx4 v[14:15], off
	s_add_i32 m0, s72, 0x4000
	s_nop 0
	global_load_lds_dwordx4 v4, s[86:87]
	s_add_i32 m0, s72, 0x4400
	s_nop 0
	global_load_lds_dwordx4 v6, s[86:87]
	s_add_i32 m0, s72, 0x8000
	s_add_u32 s84, s73, s10
	s_addc_u32 s85, s74, 0
	v_lshl_add_u64 v[14:15], s[84:85], 0, v[0:1]
	s_lshl_b32 s3, s3, 8
	v_lshl_add_u64 v[14:15], v[14:15], 0, s[18:19]
	s_add_u32 s86, s75, s3
	global_load_lds_dwordx4 v[14:15], off
	v_lshl_add_u64 v[14:15], s[84:85], 0, v[8:9]
	s_addc_u32 s87, s82, 0
	v_lshl_add_u64 v[14:15], v[14:15], 0, s[18:19]
	s_add_i32 m0, s72, 0x8400
	s_nop 0
	global_load_lds_dwordx4 v[14:15], off
	s_add_i32 m0, s72, 0xc000
	s_nop 0
	global_load_lds_dwordx4 v4, s[86:87]
	s_add_i32 m0, s72, 0xc400
	s_nop 0
	global_load_lds_dwordx4 v6, s[86:87]
	s_waitcnt vmcnt(8)
	v_and_b32_e32 v7, 0xffff0000, v98
	v_lshlrev_b32_e32 v5, 16, v98
	v_mul_f32_e32 v13, v7, v7
	v_fmac_f32_e32 v13, v5, v5
	v_lshlrev_b32_e32 v5, 16, v99
	v_fmac_f32_e32 v13, v5, v5
	v_and_b32_e32 v5, 0xffff0000, v99
	v_fmac_f32_e32 v13, v5, v5
	v_lshlrev_b32_e32 v5, 16, v100
	v_fmac_f32_e32 v13, v5, v5
	v_and_b32_e32 v5, 0xffff0000, v100
	v_fmac_f32_e32 v13, v5, v5
	v_lshlrev_b32_e32 v5, 16, v101
	v_fmac_f32_e32 v13, v5, v5
	v_and_b32_e32 v5, 0xffff0000, v101
	v_fmac_f32_e32 v13, v5, v5
	v_lshlrev_b32_e32 v5, 16, v102
	v_fmac_f32_e32 v13, v5, v5
	v_and_b32_e32 v5, 0xffff0000, v102
	v_fmac_f32_e32 v13, v5, v5
	v_lshlrev_b32_e32 v5, 16, v103
	v_fmac_f32_e32 v13, v5, v5
	v_and_b32_e32 v5, 0xffff0000, v103
	v_fmac_f32_e32 v13, v5, v5
	v_lshlrev_b32_e32 v5, 16, v104
	v_fmac_f32_e32 v13, v5, v5
	v_and_b32_e32 v5, 0xffff0000, v104
	v_fmac_f32_e32 v13, v5, v5
	v_lshlrev_b32_e32 v5, 16, v105
	v_fmac_f32_e32 v13, v5, v5
	v_and_b32_e32 v5, 0xffff0000, v105
	v_fmac_f32_e32 v13, v5, v5
	v_lshlrev_b32_e32 v5, 16, v106
	v_fmac_f32_e32 v13, v5, v5
	v_and_b32_e32 v5, 0xffff0000, v106
	v_fmac_f32_e32 v13, v5, v5
	v_lshlrev_b32_e32 v5, 16, v107
	v_fmac_f32_e32 v13, v5, v5
	v_and_b32_e32 v5, 0xffff0000, v107
	v_fmac_f32_e32 v13, v5, v5
	v_lshlrev_b32_e32 v5, 16, v108
	v_fmac_f32_e32 v13, v5, v5
	v_and_b32_e32 v5, 0xffff0000, v108
	v_fmac_f32_e32 v13, v5, v5
	v_lshlrev_b32_e32 v5, 16, v109
	v_fmac_f32_e32 v13, v5, v5
	v_and_b32_e32 v5, 0xffff0000, v109
	v_fmac_f32_e32 v13, v5, v5
	v_lshlrev_b32_e32 v5, 16, v110
	v_fmac_f32_e32 v13, v5, v5
	v_and_b32_e32 v5, 0xffff0000, v110
	v_fmac_f32_e32 v13, v5, v5
	v_lshlrev_b32_e32 v5, 16, v111
	v_fmac_f32_e32 v13, v5, v5
	v_and_b32_e32 v5, 0xffff0000, v111
	v_fmac_f32_e32 v13, v5, v5
	v_lshlrev_b32_e32 v5, 16, v112
	v_fmac_f32_e32 v13, v5, v5
	v_and_b32_e32 v5, 0xffff0000, v112
	v_fmac_f32_e32 v13, v5, v5
	v_lshlrev_b32_e32 v5, 16, v113
	v_fmac_f32_e32 v13, v5, v5
	v_and_b32_e32 v5, 0xffff0000, v113
	v_fmac_f32_e32 v13, v5, v5
	ds_bpermute_b32 v14, v115, v13
	s_cmp_eq_u32 s2, 31
	s_cbranch_scc1 .LBB0_397
	s_sub_i32 s10, s59, 64
	s_add_i32 m0, s72, 0x10000
	s_mul_i32 s2, s10, 0x3400
	s_mul_hi_u32 s3, s10, 0x3400
	s_add_u32 s2, s73, s2
	s_addc_u32 s3, s74, s3
	s_lshl_b64 s[84:85], s[10:11], 1
	v_lshl_add_u64 v[16:17], s[2:3], 0, v[0:1]
	s_add_u32 s74, s75, s84
	v_lshl_add_u64 v[16:17], v[16:17], 0, s[18:19]
	v_lshl_add_u64 v[8:9], s[2:3], 0, v[8:9]
	v_mov_b32_e32 v5, v1
	s_addc_u32 s75, s82, s85
	global_load_lds_dwordx4 v[16:17], off
	v_lshl_add_u64 v[8:9], v[8:9], 0, s[18:19]
	s_add_i32 m0, s72, 0x10400
	v_mov_b32_e32 v7, v1
	global_load_lds_dwordx4 v[8:9], off
	s_add_i32 m0, s72, 0x14000
	s_nop 0
	global_load_lds_dwordx4 v4, s[74:75]
	v_lshl_add_u64 v[4:5], s[74:75], 0, v[6:7]
	s_add_i32 m0, s72, 0x14400
	s_nop 0
	global_load_lds_dwordx4 v[4:5], off
